# ffn_out prompt rows as 128x256 double tiles (two column tiles share the A row tile, A double-buffered)
# baseline (speedup 1.0000x reference)
.LBB0_2414:
	s_lshl_b32 s16, s12, 3
	v_readlane_b32 s6, v249, 52
	s_mul_i32 s0, s72, 0xb00
	s_mov_b32 s1, s73
	s_cmp_ge_i32 s14, s16
	s_mul_hi_u32 s10, s6, 0x580000
	s_mul_i32 s11, s6, 0x580000
	v_readlane_b32 s7, v249, 53
	s_cbranch_scc1 .LBB0_2422
	s_lshr_b32 s17, s12, 3
	s_lshl_b64 s[6:7], s[0:1], 1
	s_waitcnt lgkmcnt(0)
	s_add_u32 s18, s8, s6
	s_addc_u32 s19, s9, s7
	v_and_b32_e32 v2, 15, v0
	v_ashrrev_i32_e32 v3, 1, v0
	s_movk_i32 s20, 0xffc0
	s_cmp_lt_i32 s13, 0
	v_and_or_b32 v74, v3, s20, v2
	v_lshrrev_b32_e32 v2, 2, v0
	s_cselect_b64 s[6:7], -1, 0
	v_and_b32_e32 v2, 12, v2
	s_add_u32 s20, s8, s11
	v_and_or_b32 v75, v0, 64, v2
	s_addc_u32 s21, s9, s10
	v_readlane_b32 s24, v249, 1
	s_nop 0
	s_cmpk_lg_u32 s24, 0x200
	s_cbranch_scc1 .LBB0_2417
	s_load_dwordx2 s[38:39], s[84:85], 0x130
	v_readlane_b32 s24, v249, 0
	s_nop 0
	s_and_b32 s25, s24, 7
	s_lshr_b32 s24, s24, 3
	s_and_b32 s28, s24, 15
	s_lshr_b32 s27, s24, 4
	s_lshl_b32 s28, s28, 3
	s_add_i32 s28, s28, s25
	s_add_i32 s29, s27, 4
	s_mul_i32 s24, s28, 0xb0000
	s_add_u32 s30, s4, s24
	s_addc_u32 s31, s5, 0
	s_mul_i32 s24, s27, 0xb0000
	s_add_u32 s44, s20, s24
	s_addc_u32 s45, s21, 0
	s_mul_i32 s24, s29, 0xb0000
	s_add_u32 s34, s20, s24
	s_addc_u32 s35, s21, 0
	s_waitcnt lgkmcnt(0)
	s_lshl_b32 s24, s28, 19
	s_lshl_b32 s27, s27, 9
	s_add_i32 s27, s24, s27
	s_add_u32 s40, s38, s27
	s_addc_u32 s41, s39, 0
	s_lshl_b32 s29, s29, 9
	s_add_i32 s29, s24, s29
	s_add_u32 s42, s38, s29
	s_addc_u32 s43, s39, 0
	v_and_b32_e32 v144, 7, v196
	v_bfe_u32 v145, v196, 4, 2
	v_bfe_u32 v146, v196, 6, 1
	v_lshl_or_b32 v147, v146, 2, v145
	v_xor_b32_e32 v144, v144, v147
	v_lshrrev_b32_e32 v147, 3, v196
	v_mul_u32_u24_e32 v147, 0x1600, v147
	v_lshl_or_b32 v136, v144, 4, v147
	v_add_u32_e32 v137, 0x2c000, v136
	v_add_u32_e32 v138, 0x58000, v136
	v_add_u32_e32 v139, 0x84000, v136
	v_and_b32_e32 v144, 15, v196
	v_bfe_u32 v147, v196, 1, 3
	v_xor_b32_e32 v147, v145, v147
	v_lshlrev_b32_e32 v147, 4, v147
	v_xor_b32_e32 v130, 64, v147
	v_lshlrev_b32_e32 v144, 7, v144
	v_lshrrev_b32_e32 v131, 7, v196
	v_lshl_or_b32 v131, v131, 13, v144
	v_lshl_or_b32 v133, v146, 13, v144
	v_add_u32_e32 v140, v131, v147
	v_add_u32_e32 v141, v131, v130
	v_add_u32_e32 v142, v133, v147
	v_add_u32_e32 v143, v133, v130
	v_readfirstlane_b32 s36, v196
	s_lshr_b32 s36, s36, 6
	s_lshl_b32 s36, s36, 10
	s_barrier
	s_add_i32 m0, s36, 0x0
	s_nop 0
	global_load_lds_dwordx4 v136, s[30:31]
	s_add_i32 m0, s36, 0x1000
	s_nop 0
	global_load_lds_dwordx4 v137, s[30:31]
	s_add_i32 m0, s36, 0x2000
	s_nop 0
	global_load_lds_dwordx4 v138, s[30:31]
	s_add_i32 m0, s36, 0x3000
	s_nop 0
	global_load_lds_dwordx4 v139, s[30:31]
	s_add_u32 s30, s30, 0x80
	s_addc_u32 s31, s31, 0
	s_add_i32 m0, s36, 0x8000
	s_nop 0
	global_load_lds_dwordx4 v136, s[44:45]
	s_add_i32 m0, s36, 0x9000
	s_nop 0
	global_load_lds_dwordx4 v137, s[44:45]
	s_add_i32 m0, s36, 0xa000
	s_nop 0
	global_load_lds_dwordx4 v138, s[44:45]
	s_add_i32 m0, s36, 0xb000
	s_nop 0
	global_load_lds_dwordx4 v139, s[44:45]
	s_add_i32 m0, s36, 0xc000
	s_nop 0
	global_load_lds_dwordx4 v136, s[34:35]
	s_add_i32 m0, s36, 0xd000
	s_nop 0
	global_load_lds_dwordx4 v137, s[34:35]
	s_add_i32 m0, s36, 0xe000
	s_nop 0
	global_load_lds_dwordx4 v138, s[34:35]
	s_add_i32 m0, s36, 0xf000
	s_nop 0
	global_load_lds_dwordx4 v139, s[34:35]
	s_add_u32 s44, s44, 0x80
	s_addc_u32 s45, s45, 0
	s_add_u32 s34, s34, 0x80
	s_addc_u32 s35, s35, 0
	v_mov_b64_e32 v[62:63], 0
	v_mov_b64_e32 v[64:65], 0
	v_mov_b64_e32 v[58:59], 0
	v_mov_b64_e32 v[60:61], 0
	v_mov_b64_e32 v[54:55], 0
	v_mov_b64_e32 v[56:57], 0
	v_mov_b64_e32 v[50:51], 0
	v_mov_b64_e32 v[52:53], 0
	v_mov_b64_e32 v[46:47], 0
	v_mov_b64_e32 v[48:49], 0
	v_mov_b64_e32 v[42:43], 0
	v_mov_b64_e32 v[44:45], 0
	v_mov_b64_e32 v[38:39], 0
	v_mov_b64_e32 v[40:41], 0
	v_mov_b64_e32 v[34:35], 0
	v_mov_b64_e32 v[36:37], 0
	v_mov_b64_e32 v[30:31], 0
	v_mov_b64_e32 v[32:33], 0
	v_mov_b64_e32 v[26:27], 0
	v_mov_b64_e32 v[28:29], 0
	v_mov_b64_e32 v[22:23], 0
	v_mov_b64_e32 v[24:25], 0
	v_mov_b64_e32 v[18:19], 0
	v_mov_b64_e32 v[20:21], 0
	v_mov_b64_e32 v[14:15], 0
	v_mov_b64_e32 v[16:17], 0
	v_mov_b64_e32 v[10:11], 0
	v_mov_b64_e32 v[12:13], 0
	v_mov_b64_e32 v[6:7], 0
	v_mov_b64_e32 v[8:9], 0
	v_mov_b64_e32 v[2:3], 0
	v_mov_b64_e32 v[4:5], 0
	v_mov_b64_e32 v[66:67], 0
	v_mov_b64_e32 v[68:69], 0
	v_mov_b64_e32 v[70:71], 0
	v_mov_b64_e32 v[72:73], 0
	v_mov_b64_e32 v[74:75], 0
	v_mov_b64_e32 v[76:77], 0
	v_mov_b64_e32 v[78:79], 0
	v_mov_b64_e32 v[80:81], 0
	v_mov_b64_e32 v[82:83], 0
	v_mov_b64_e32 v[84:85], 0
	v_mov_b64_e32 v[86:87], 0
	v_mov_b64_e32 v[88:89], 0
	v_mov_b64_e32 v[90:91], 0
	v_mov_b64_e32 v[92:93], 0
	v_mov_b64_e32 v[94:95], 0
	v_mov_b64_e32 v[96:97], 0
	v_mov_b64_e32 v[98:99], 0
	v_mov_b64_e32 v[100:101], 0
	v_mov_b64_e32 v[102:103], 0
	v_mov_b64_e32 v[104:105], 0
	v_mov_b64_e32 v[106:107], 0
	v_mov_b64_e32 v[108:109], 0
	v_mov_b64_e32 v[110:111], 0
	v_mov_b64_e32 v[112:113], 0
	v_mov_b64_e32 v[114:115], 0
	v_mov_b64_e32 v[116:117], 0
	v_mov_b64_e32 v[118:119], 0
	v_mov_b64_e32 v[120:121], 0
	v_mov_b64_e32 v[122:123], 0
	v_mov_b64_e32 v[124:125], 0
	v_mov_b64_e32 v[126:127], 0
	v_mov_b64_e32 v[128:129], 0
	s_movk_i32 s37, 21
.Lr2p_k:
	s_waitcnt vmcnt(0)
	s_barrier
	s_add_i32 m0, s36, 0x4000
	s_nop 0
	global_load_lds_dwordx4 v136, s[30:31]
	s_add_i32 m0, s36, 0x5000
	s_nop 0
	global_load_lds_dwordx4 v137, s[30:31]
	s_add_i32 m0, s36, 0x6000
	s_nop 0
	global_load_lds_dwordx4 v138, s[30:31]
	s_add_i32 m0, s36, 0x7000
	s_nop 0
	global_load_lds_dwordx4 v139, s[30:31]
	s_add_u32 s30, s30, 0x80
	s_addc_u32 s31, s31, 0
	ds_read_b128 v[148:151], v140 offset:0
	ds_read_b128 v[152:155], v140 offset:2048
	ds_read_b128 v[156:159], v140 offset:4096
	ds_read_b128 v[160:163], v140 offset:6144
	ds_read_b128 v[164:167], v142 offset:32768
	ds_read_b128 v[168:171], v142 offset:34816
	ds_read_b128 v[174:177], v142 offset:36864
	ds_read_b128 v[182:185], v142 offset:38912
	ds_read_b128 v[188:191], v142 offset:49152
	ds_read_b128 v[192:195], v142 offset:51200
	ds_read_b128 v[208:211], v142 offset:53248
	ds_read_b128 v[212:215], v142 offset:55296
	s_waitcnt lgkmcnt(0)
	s_setprio 1
	v_mfma_f32_16x16x32_bf16 v[62:65], v[164:167], v[148:151], v[62:65]
	v_mfma_f32_16x16x32_bf16 v[58:61], v[168:171], v[148:151], v[58:61]
	v_mfma_f32_16x16x32_bf16 v[54:57], v[174:177], v[148:151], v[54:57]
	v_mfma_f32_16x16x32_bf16 v[50:53], v[182:185], v[148:151], v[50:53]
	v_mfma_f32_16x16x32_bf16 v[46:49], v[164:167], v[152:155], v[46:49]
	v_mfma_f32_16x16x32_bf16 v[42:45], v[168:171], v[152:155], v[42:45]
	v_mfma_f32_16x16x32_bf16 v[38:41], v[174:177], v[152:155], v[38:41]
	v_mfma_f32_16x16x32_bf16 v[34:37], v[182:185], v[152:155], v[34:37]
	v_mfma_f32_16x16x32_bf16 v[30:33], v[164:167], v[156:159], v[30:33]
	v_mfma_f32_16x16x32_bf16 v[26:29], v[168:171], v[156:159], v[26:29]
	v_mfma_f32_16x16x32_bf16 v[22:25], v[174:177], v[156:159], v[22:25]
	v_mfma_f32_16x16x32_bf16 v[18:21], v[182:185], v[156:159], v[18:21]
	v_mfma_f32_16x16x32_bf16 v[14:17], v[164:167], v[160:163], v[14:17]
	v_mfma_f32_16x16x32_bf16 v[10:13], v[168:171], v[160:163], v[10:13]
	v_mfma_f32_16x16x32_bf16 v[6:9], v[174:177], v[160:163], v[6:9]
	v_mfma_f32_16x16x32_bf16 v[2:5], v[182:185], v[160:163], v[2:5]
	v_mfma_f32_16x16x32_bf16 v[66:69], v[188:191], v[148:151], v[66:69]
	v_mfma_f32_16x16x32_bf16 v[70:73], v[192:195], v[148:151], v[70:73]
	v_mfma_f32_16x16x32_bf16 v[74:77], v[208:211], v[148:151], v[74:77]
	v_mfma_f32_16x16x32_bf16 v[78:81], v[212:215], v[148:151], v[78:81]
	v_mfma_f32_16x16x32_bf16 v[82:85], v[188:191], v[152:155], v[82:85]
	v_mfma_f32_16x16x32_bf16 v[86:89], v[192:195], v[152:155], v[86:89]
	v_mfma_f32_16x16x32_bf16 v[90:93], v[208:211], v[152:155], v[90:93]
	v_mfma_f32_16x16x32_bf16 v[94:97], v[212:215], v[152:155], v[94:97]
	v_mfma_f32_16x16x32_bf16 v[98:101], v[188:191], v[156:159], v[98:101]
	v_mfma_f32_16x16x32_bf16 v[102:105], v[192:195], v[156:159], v[102:105]
	v_mfma_f32_16x16x32_bf16 v[106:109], v[208:211], v[156:159], v[106:109]
	v_mfma_f32_16x16x32_bf16 v[110:113], v[212:215], v[156:159], v[110:113]
	v_mfma_f32_16x16x32_bf16 v[114:117], v[188:191], v[160:163], v[114:117]
	v_mfma_f32_16x16x32_bf16 v[118:121], v[192:195], v[160:163], v[118:121]
	v_mfma_f32_16x16x32_bf16 v[122:125], v[208:211], v[160:163], v[122:125]
	v_mfma_f32_16x16x32_bf16 v[126:129], v[212:215], v[160:163], v[126:129]
	s_setprio 0
	ds_read_b128 v[148:151], v141 offset:0
	ds_read_b128 v[152:155], v141 offset:2048
	ds_read_b128 v[156:159], v141 offset:4096
	ds_read_b128 v[160:163], v141 offset:6144
	ds_read_b128 v[164:167], v143 offset:32768
	ds_read_b128 v[168:171], v143 offset:34816
	ds_read_b128 v[174:177], v143 offset:36864
	ds_read_b128 v[182:185], v143 offset:38912
	ds_read_b128 v[188:191], v143 offset:49152
	ds_read_b128 v[192:195], v143 offset:51200
	ds_read_b128 v[208:211], v143 offset:53248
	ds_read_b128 v[212:215], v143 offset:55296
	s_waitcnt lgkmcnt(0)
	s_barrier
	s_add_i32 m0, s36, 0x8000
	s_nop 0
	global_load_lds_dwordx4 v136, s[44:45]
	s_add_i32 m0, s36, 0x9000
	s_nop 0
	global_load_lds_dwordx4 v137, s[44:45]
	s_add_i32 m0, s36, 0xa000
	s_nop 0
	global_load_lds_dwordx4 v138, s[44:45]
	s_add_i32 m0, s36, 0xb000
	s_nop 0
	global_load_lds_dwordx4 v139, s[44:45]
	s_add_i32 m0, s36, 0xc000
	s_nop 0
	global_load_lds_dwordx4 v136, s[34:35]
	s_add_i32 m0, s36, 0xd000
	s_nop 0
	global_load_lds_dwordx4 v137, s[34:35]
	s_add_i32 m0, s36, 0xe000
	s_nop 0
	global_load_lds_dwordx4 v138, s[34:35]
	s_add_i32 m0, s36, 0xf000
	s_nop 0
	global_load_lds_dwordx4 v139, s[34:35]
	s_add_u32 s44, s44, 0x80
	s_addc_u32 s45, s45, 0
	s_add_u32 s34, s34, 0x80
	s_addc_u32 s35, s35, 0
	s_setprio 1
	v_mfma_f32_16x16x32_bf16 v[62:65], v[164:167], v[148:151], v[62:65]
	v_mfma_f32_16x16x32_bf16 v[58:61], v[168:171], v[148:151], v[58:61]
	v_mfma_f32_16x16x32_bf16 v[54:57], v[174:177], v[148:151], v[54:57]
	v_mfma_f32_16x16x32_bf16 v[50:53], v[182:185], v[148:151], v[50:53]
	v_mfma_f32_16x16x32_bf16 v[46:49], v[164:167], v[152:155], v[46:49]
	v_mfma_f32_16x16x32_bf16 v[42:45], v[168:171], v[152:155], v[42:45]
	v_mfma_f32_16x16x32_bf16 v[38:41], v[174:177], v[152:155], v[38:41]
	v_mfma_f32_16x16x32_bf16 v[34:37], v[182:185], v[152:155], v[34:37]
	v_mfma_f32_16x16x32_bf16 v[30:33], v[164:167], v[156:159], v[30:33]
	v_mfma_f32_16x16x32_bf16 v[26:29], v[168:171], v[156:159], v[26:29]
	v_mfma_f32_16x16x32_bf16 v[22:25], v[174:177], v[156:159], v[22:25]
	v_mfma_f32_16x16x32_bf16 v[18:21], v[182:185], v[156:159], v[18:21]
	v_mfma_f32_16x16x32_bf16 v[14:17], v[164:167], v[160:163], v[14:17]
	v_mfma_f32_16x16x32_bf16 v[10:13], v[168:171], v[160:163], v[10:13]
	v_mfma_f32_16x16x32_bf16 v[6:9], v[174:177], v[160:163], v[6:9]
	v_mfma_f32_16x16x32_bf16 v[2:5], v[182:185], v[160:163], v[2:5]
	v_mfma_f32_16x16x32_bf16 v[66:69], v[188:191], v[148:151], v[66:69]
	v_mfma_f32_16x16x32_bf16 v[70:73], v[192:195], v[148:151], v[70:73]
	v_mfma_f32_16x16x32_bf16 v[74:77], v[208:211], v[148:151], v[74:77]
	v_mfma_f32_16x16x32_bf16 v[78:81], v[212:215], v[148:151], v[78:81]
	v_mfma_f32_16x16x32_bf16 v[82:85], v[188:191], v[152:155], v[82:85]
	v_mfma_f32_16x16x32_bf16 v[86:89], v[192:195], v[152:155], v[86:89]
	v_mfma_f32_16x16x32_bf16 v[90:93], v[208:211], v[152:155], v[90:93]
	v_mfma_f32_16x16x32_bf16 v[94:97], v[212:215], v[152:155], v[94:97]
	v_mfma_f32_16x16x32_bf16 v[98:101], v[188:191], v[156:159], v[98:101]
	v_mfma_f32_16x16x32_bf16 v[102:105], v[192:195], v[156:159], v[102:105]
	v_mfma_f32_16x16x32_bf16 v[106:109], v[208:211], v[156:159], v[106:109]
	v_mfma_f32_16x16x32_bf16 v[110:113], v[212:215], v[156:159], v[110:113]
	v_mfma_f32_16x16x32_bf16 v[114:117], v[188:191], v[160:163], v[114:117]
	v_mfma_f32_16x16x32_bf16 v[118:121], v[192:195], v[160:163], v[118:121]
	v_mfma_f32_16x16x32_bf16 v[122:125], v[208:211], v[160:163], v[122:125]
	v_mfma_f32_16x16x32_bf16 v[126:129], v[212:215], v[160:163], v[126:129]
	s_setprio 0
	s_waitcnt vmcnt(0)
	s_barrier
	s_add_i32 m0, s36, 0x0
	s_nop 0
	global_load_lds_dwordx4 v136, s[30:31]
	s_add_i32 m0, s36, 0x1000
	s_nop 0
	global_load_lds_dwordx4 v137, s[30:31]
	s_add_i32 m0, s36, 0x2000
	s_nop 0
	global_load_lds_dwordx4 v138, s[30:31]
	s_add_i32 m0, s36, 0x3000
	s_nop 0
	global_load_lds_dwordx4 v139, s[30:31]
	s_add_u32 s30, s30, 0x80
	s_addc_u32 s31, s31, 0
	ds_read_b128 v[148:151], v140 offset:16384
	ds_read_b128 v[152:155], v140 offset:18432
	ds_read_b128 v[156:159], v140 offset:20480
	ds_read_b128 v[160:163], v140 offset:22528
	ds_read_b128 v[164:167], v142 offset:32768
	ds_read_b128 v[168:171], v142 offset:34816
	ds_read_b128 v[174:177], v142 offset:36864
	ds_read_b128 v[182:185], v142 offset:38912
	ds_read_b128 v[188:191], v142 offset:49152
	ds_read_b128 v[192:195], v142 offset:51200
	ds_read_b128 v[208:211], v142 offset:53248
	ds_read_b128 v[212:215], v142 offset:55296
	s_waitcnt lgkmcnt(0)
	s_setprio 1
	v_mfma_f32_16x16x32_bf16 v[62:65], v[164:167], v[148:151], v[62:65]
	v_mfma_f32_16x16x32_bf16 v[58:61], v[168:171], v[148:151], v[58:61]
	v_mfma_f32_16x16x32_bf16 v[54:57], v[174:177], v[148:151], v[54:57]
	v_mfma_f32_16x16x32_bf16 v[50:53], v[182:185], v[148:151], v[50:53]
	v_mfma_f32_16x16x32_bf16 v[46:49], v[164:167], v[152:155], v[46:49]
	v_mfma_f32_16x16x32_bf16 v[42:45], v[168:171], v[152:155], v[42:45]
	v_mfma_f32_16x16x32_bf16 v[38:41], v[174:177], v[152:155], v[38:41]
	v_mfma_f32_16x16x32_bf16 v[34:37], v[182:185], v[152:155], v[34:37]
	v_mfma_f32_16x16x32_bf16 v[30:33], v[164:167], v[156:159], v[30:33]
	v_mfma_f32_16x16x32_bf16 v[26:29], v[168:171], v[156:159], v[26:29]
	v_mfma_f32_16x16x32_bf16 v[22:25], v[174:177], v[156:159], v[22:25]
	v_mfma_f32_16x16x32_bf16 v[18:21], v[182:185], v[156:159], v[18:21]
	v_mfma_f32_16x16x32_bf16 v[14:17], v[164:167], v[160:163], v[14:17]
	v_mfma_f32_16x16x32_bf16 v[10:13], v[168:171], v[160:163], v[10:13]
	v_mfma_f32_16x16x32_bf16 v[6:9], v[174:177], v[160:163], v[6:9]
	v_mfma_f32_16x16x32_bf16 v[2:5], v[182:185], v[160:163], v[2:5]
	v_mfma_f32_16x16x32_bf16 v[66:69], v[188:191], v[148:151], v[66:69]
	v_mfma_f32_16x16x32_bf16 v[70:73], v[192:195], v[148:151], v[70:73]
	v_mfma_f32_16x16x32_bf16 v[74:77], v[208:211], v[148:151], v[74:77]
	v_mfma_f32_16x16x32_bf16 v[78:81], v[212:215], v[148:151], v[78:81]
	v_mfma_f32_16x16x32_bf16 v[82:85], v[188:191], v[152:155], v[82:85]
	v_mfma_f32_16x16x32_bf16 v[86:89], v[192:195], v[152:155], v[86:89]
	v_mfma_f32_16x16x32_bf16 v[90:93], v[208:211], v[152:155], v[90:93]
	v_mfma_f32_16x16x32_bf16 v[94:97], v[212:215], v[152:155], v[94:97]
	v_mfma_f32_16x16x32_bf16 v[98:101], v[188:191], v[156:159], v[98:101]
	v_mfma_f32_16x16x32_bf16 v[102:105], v[192:195], v[156:159], v[102:105]
	v_mfma_f32_16x16x32_bf16 v[106:109], v[208:211], v[156:159], v[106:109]
	v_mfma_f32_16x16x32_bf16 v[110:113], v[212:215], v[156:159], v[110:113]
	v_mfma_f32_16x16x32_bf16 v[114:117], v[188:191], v[160:163], v[114:117]
	v_mfma_f32_16x16x32_bf16 v[118:121], v[192:195], v[160:163], v[118:121]
	v_mfma_f32_16x16x32_bf16 v[122:125], v[208:211], v[160:163], v[122:125]
	v_mfma_f32_16x16x32_bf16 v[126:129], v[212:215], v[160:163], v[126:129]
	s_setprio 0
	ds_read_b128 v[148:151], v141 offset:16384
	ds_read_b128 v[152:155], v141 offset:18432
	ds_read_b128 v[156:159], v141 offset:20480
	ds_read_b128 v[160:163], v141 offset:22528
	ds_read_b128 v[164:167], v143 offset:32768
	ds_read_b128 v[168:171], v143 offset:34816
	ds_read_b128 v[174:177], v143 offset:36864
	ds_read_b128 v[182:185], v143 offset:38912
	ds_read_b128 v[188:191], v143 offset:49152
	ds_read_b128 v[192:195], v143 offset:51200
	ds_read_b128 v[208:211], v143 offset:53248
	ds_read_b128 v[212:215], v143 offset:55296
	s_waitcnt lgkmcnt(0)
	s_barrier
	s_add_i32 m0, s36, 0x8000
	s_nop 0
	global_load_lds_dwordx4 v136, s[44:45]
	s_add_i32 m0, s36, 0x9000
	s_nop 0
	global_load_lds_dwordx4 v137, s[44:45]
	s_add_i32 m0, s36, 0xa000
	s_nop 0
	global_load_lds_dwordx4 v138, s[44:45]
	s_add_i32 m0, s36, 0xb000
	s_nop 0
	global_load_lds_dwordx4 v139, s[44:45]
	s_add_i32 m0, s36, 0xc000
	s_nop 0
	global_load_lds_dwordx4 v136, s[34:35]
	s_add_i32 m0, s36, 0xd000
	s_nop 0
	global_load_lds_dwordx4 v137, s[34:35]
	s_add_i32 m0, s36, 0xe000
	s_nop 0
	global_load_lds_dwordx4 v138, s[34:35]
	s_add_i32 m0, s36, 0xf000
	s_nop 0
	global_load_lds_dwordx4 v139, s[34:35]
	s_add_u32 s44, s44, 0x80
	s_addc_u32 s45, s45, 0
	s_add_u32 s34, s34, 0x80
	s_addc_u32 s35, s35, 0
	s_setprio 1
	v_mfma_f32_16x16x32_bf16 v[62:65], v[164:167], v[148:151], v[62:65]
	v_mfma_f32_16x16x32_bf16 v[58:61], v[168:171], v[148:151], v[58:61]
	v_mfma_f32_16x16x32_bf16 v[54:57], v[174:177], v[148:151], v[54:57]
	v_mfma_f32_16x16x32_bf16 v[50:53], v[182:185], v[148:151], v[50:53]
	v_mfma_f32_16x16x32_bf16 v[46:49], v[164:167], v[152:155], v[46:49]
	v_mfma_f32_16x16x32_bf16 v[42:45], v[168:171], v[152:155], v[42:45]
	v_mfma_f32_16x16x32_bf16 v[38:41], v[174:177], v[152:155], v[38:41]
	v_mfma_f32_16x16x32_bf16 v[34:37], v[182:185], v[152:155], v[34:37]
	v_mfma_f32_16x16x32_bf16 v[30:33], v[164:167], v[156:159], v[30:33]
	v_mfma_f32_16x16x32_bf16 v[26:29], v[168:171], v[156:159], v[26:29]
	v_mfma_f32_16x16x32_bf16 v[22:25], v[174:177], v[156:159], v[22:25]
	v_mfma_f32_16x16x32_bf16 v[18:21], v[182:185], v[156:159], v[18:21]
	v_mfma_f32_16x16x32_bf16 v[14:17], v[164:167], v[160:163], v[14:17]
	v_mfma_f32_16x16x32_bf16 v[10:13], v[168:171], v[160:163], v[10:13]
	v_mfma_f32_16x16x32_bf16 v[6:9], v[174:177], v[160:163], v[6:9]
	v_mfma_f32_16x16x32_bf16 v[2:5], v[182:185], v[160:163], v[2:5]
	v_mfma_f32_16x16x32_bf16 v[66:69], v[188:191], v[148:151], v[66:69]
	v_mfma_f32_16x16x32_bf16 v[70:73], v[192:195], v[148:151], v[70:73]
	v_mfma_f32_16x16x32_bf16 v[74:77], v[208:211], v[148:151], v[74:77]
	v_mfma_f32_16x16x32_bf16 v[78:81], v[212:215], v[148:151], v[78:81]
	v_mfma_f32_16x16x32_bf16 v[82:85], v[188:191], v[152:155], v[82:85]
	v_mfma_f32_16x16x32_bf16 v[86:89], v[192:195], v[152:155], v[86:89]
	v_mfma_f32_16x16x32_bf16 v[90:93], v[208:211], v[152:155], v[90:93]
	v_mfma_f32_16x16x32_bf16 v[94:97], v[212:215], v[152:155], v[94:97]
	v_mfma_f32_16x16x32_bf16 v[98:101], v[188:191], v[156:159], v[98:101]
	v_mfma_f32_16x16x32_bf16 v[102:105], v[192:195], v[156:159], v[102:105]
	v_mfma_f32_16x16x32_bf16 v[106:109], v[208:211], v[156:159], v[106:109]
	v_mfma_f32_16x16x32_bf16 v[110:113], v[212:215], v[156:159], v[110:113]
	v_mfma_f32_16x16x32_bf16 v[114:117], v[188:191], v[160:163], v[114:117]
	v_mfma_f32_16x16x32_bf16 v[118:121], v[192:195], v[160:163], v[118:121]
	v_mfma_f32_16x16x32_bf16 v[122:125], v[208:211], v[160:163], v[122:125]
	v_mfma_f32_16x16x32_bf16 v[126:129], v[212:215], v[160:163], v[126:129]
	s_setprio 0
	s_add_i32 s37, s37, -1
	s_cmp_lg_u32 s37, 0
	s_cbranch_scc1 .Lr2p_k
	s_waitcnt vmcnt(0)
	s_barrier
	s_add_i32 m0, s36, 0x4000
	s_nop 0
	global_load_lds_dwordx4 v136, s[30:31]
	s_add_i32 m0, s36, 0x5000
	s_nop 0
	global_load_lds_dwordx4 v137, s[30:31]
	s_add_i32 m0, s36, 0x6000
	s_nop 0
	global_load_lds_dwordx4 v138, s[30:31]
	s_add_i32 m0, s36, 0x7000
	s_nop 0
	global_load_lds_dwordx4 v139, s[30:31]
	s_add_u32 s30, s30, 0x80
	s_addc_u32 s31, s31, 0
	ds_read_b128 v[148:151], v140 offset:0
	ds_read_b128 v[152:155], v140 offset:2048
	ds_read_b128 v[156:159], v140 offset:4096
	ds_read_b128 v[160:163], v140 offset:6144
	ds_read_b128 v[164:167], v142 offset:32768
	ds_read_b128 v[168:171], v142 offset:34816
	ds_read_b128 v[174:177], v142 offset:36864
	ds_read_b128 v[182:185], v142 offset:38912
	ds_read_b128 v[188:191], v142 offset:49152
	ds_read_b128 v[192:195], v142 offset:51200
	ds_read_b128 v[208:211], v142 offset:53248
	ds_read_b128 v[212:215], v142 offset:55296
	s_waitcnt lgkmcnt(0)
	s_setprio 1
	v_mfma_f32_16x16x32_bf16 v[62:65], v[164:167], v[148:151], v[62:65]
	v_mfma_f32_16x16x32_bf16 v[58:61], v[168:171], v[148:151], v[58:61]
	v_mfma_f32_16x16x32_bf16 v[54:57], v[174:177], v[148:151], v[54:57]
	v_mfma_f32_16x16x32_bf16 v[50:53], v[182:185], v[148:151], v[50:53]
	v_mfma_f32_16x16x32_bf16 v[46:49], v[164:167], v[152:155], v[46:49]
	v_mfma_f32_16x16x32_bf16 v[42:45], v[168:171], v[152:155], v[42:45]
	v_mfma_f32_16x16x32_bf16 v[38:41], v[174:177], v[152:155], v[38:41]
	v_mfma_f32_16x16x32_bf16 v[34:37], v[182:185], v[152:155], v[34:37]
	v_mfma_f32_16x16x32_bf16 v[30:33], v[164:167], v[156:159], v[30:33]
	v_mfma_f32_16x16x32_bf16 v[26:29], v[168:171], v[156:159], v[26:29]
	v_mfma_f32_16x16x32_bf16 v[22:25], v[174:177], v[156:159], v[22:25]
	v_mfma_f32_16x16x32_bf16 v[18:21], v[182:185], v[156:159], v[18:21]
	v_mfma_f32_16x16x32_bf16 v[14:17], v[164:167], v[160:163], v[14:17]
	v_mfma_f32_16x16x32_bf16 v[10:13], v[168:171], v[160:163], v[10:13]
	v_mfma_f32_16x16x32_bf16 v[6:9], v[174:177], v[160:163], v[6:9]
	v_mfma_f32_16x16x32_bf16 v[2:5], v[182:185], v[160:163], v[2:5]
	v_mfma_f32_16x16x32_bf16 v[66:69], v[188:191], v[148:151], v[66:69]
	v_mfma_f32_16x16x32_bf16 v[70:73], v[192:195], v[148:151], v[70:73]
	v_mfma_f32_16x16x32_bf16 v[74:77], v[208:211], v[148:151], v[74:77]
	v_mfma_f32_16x16x32_bf16 v[78:81], v[212:215], v[148:151], v[78:81]
	v_mfma_f32_16x16x32_bf16 v[82:85], v[188:191], v[152:155], v[82:85]
	v_mfma_f32_16x16x32_bf16 v[86:89], v[192:195], v[152:155], v[86:89]
	v_mfma_f32_16x16x32_bf16 v[90:93], v[208:211], v[152:155], v[90:93]
	v_mfma_f32_16x16x32_bf16 v[94:97], v[212:215], v[152:155], v[94:97]
	v_mfma_f32_16x16x32_bf16 v[98:101], v[188:191], v[156:159], v[98:101]
	v_mfma_f32_16x16x32_bf16 v[102:105], v[192:195], v[156:159], v[102:105]
	v_mfma_f32_16x16x32_bf16 v[106:109], v[208:211], v[156:159], v[106:109]
	v_mfma_f32_16x16x32_bf16 v[110:113], v[212:215], v[156:159], v[110:113]
	v_mfma_f32_16x16x32_bf16 v[114:117], v[188:191], v[160:163], v[114:117]
	v_mfma_f32_16x16x32_bf16 v[118:121], v[192:195], v[160:163], v[118:121]
	v_mfma_f32_16x16x32_bf16 v[122:125], v[208:211], v[160:163], v[122:125]
	v_mfma_f32_16x16x32_bf16 v[126:129], v[212:215], v[160:163], v[126:129]
	s_setprio 0
	ds_read_b128 v[148:151], v141 offset:0
	ds_read_b128 v[152:155], v141 offset:2048
	ds_read_b128 v[156:159], v141 offset:4096
	ds_read_b128 v[160:163], v141 offset:6144
	ds_read_b128 v[164:167], v143 offset:32768
	ds_read_b128 v[168:171], v143 offset:34816
	ds_read_b128 v[174:177], v143 offset:36864
	ds_read_b128 v[182:185], v143 offset:38912
	ds_read_b128 v[188:191], v143 offset:49152
	ds_read_b128 v[192:195], v143 offset:51200
	ds_read_b128 v[208:211], v143 offset:53248
	ds_read_b128 v[212:215], v143 offset:55296
	s_waitcnt lgkmcnt(0)
	s_barrier
	s_add_i32 m0, s36, 0x8000
	s_nop 0
	global_load_lds_dwordx4 v136, s[44:45]
	s_add_i32 m0, s36, 0x9000
	s_nop 0
	global_load_lds_dwordx4 v137, s[44:45]
	s_add_i32 m0, s36, 0xa000
	s_nop 0
	global_load_lds_dwordx4 v138, s[44:45]
	s_add_i32 m0, s36, 0xb000
	s_nop 0
	global_load_lds_dwordx4 v139, s[44:45]
	s_add_i32 m0, s36, 0xc000
	s_nop 0
	global_load_lds_dwordx4 v136, s[34:35]
	s_add_i32 m0, s36, 0xd000
	s_nop 0
	global_load_lds_dwordx4 v137, s[34:35]
	s_add_i32 m0, s36, 0xe000
	s_nop 0
	global_load_lds_dwordx4 v138, s[34:35]
	s_add_i32 m0, s36, 0xf000
	s_nop 0
	global_load_lds_dwordx4 v139, s[34:35]
	s_add_u32 s44, s44, 0x80
	s_addc_u32 s45, s45, 0
	s_add_u32 s34, s34, 0x80
	s_addc_u32 s35, s35, 0
	s_setprio 1
	v_mfma_f32_16x16x32_bf16 v[62:65], v[164:167], v[148:151], v[62:65]
	v_mfma_f32_16x16x32_bf16 v[58:61], v[168:171], v[148:151], v[58:61]
	v_mfma_f32_16x16x32_bf16 v[54:57], v[174:177], v[148:151], v[54:57]
	v_mfma_f32_16x16x32_bf16 v[50:53], v[182:185], v[148:151], v[50:53]
	v_mfma_f32_16x16x32_bf16 v[46:49], v[164:167], v[152:155], v[46:49]
	v_mfma_f32_16x16x32_bf16 v[42:45], v[168:171], v[152:155], v[42:45]
	v_mfma_f32_16x16x32_bf16 v[38:41], v[174:177], v[152:155], v[38:41]
	v_mfma_f32_16x16x32_bf16 v[34:37], v[182:185], v[152:155], v[34:37]
	v_mfma_f32_16x16x32_bf16 v[30:33], v[164:167], v[156:159], v[30:33]
	v_mfma_f32_16x16x32_bf16 v[26:29], v[168:171], v[156:159], v[26:29]
	v_mfma_f32_16x16x32_bf16 v[22:25], v[174:177], v[156:159], v[22:25]
	v_mfma_f32_16x16x32_bf16 v[18:21], v[182:185], v[156:159], v[18:21]
	v_mfma_f32_16x16x32_bf16 v[14:17], v[164:167], v[160:163], v[14:17]
	v_mfma_f32_16x16x32_bf16 v[10:13], v[168:171], v[160:163], v[10:13]
	v_mfma_f32_16x16x32_bf16 v[6:9], v[174:177], v[160:163], v[6:9]
	v_mfma_f32_16x16x32_bf16 v[2:5], v[182:185], v[160:163], v[2:5]
	v_mfma_f32_16x16x32_bf16 v[66:69], v[188:191], v[148:151], v[66:69]
	v_mfma_f32_16x16x32_bf16 v[70:73], v[192:195], v[148:151], v[70:73]
	v_mfma_f32_16x16x32_bf16 v[74:77], v[208:211], v[148:151], v[74:77]
	v_mfma_f32_16x16x32_bf16 v[78:81], v[212:215], v[148:151], v[78:81]
	v_mfma_f32_16x16x32_bf16 v[82:85], v[188:191], v[152:155], v[82:85]
	v_mfma_f32_16x16x32_bf16 v[86:89], v[192:195], v[152:155], v[86:89]
	v_mfma_f32_16x16x32_bf16 v[90:93], v[208:211], v[152:155], v[90:93]
	v_mfma_f32_16x16x32_bf16 v[94:97], v[212:215], v[152:155], v[94:97]
	v_mfma_f32_16x16x32_bf16 v[98:101], v[188:191], v[156:159], v[98:101]
	v_mfma_f32_16x16x32_bf16 v[102:105], v[192:195], v[156:159], v[102:105]
	v_mfma_f32_16x16x32_bf16 v[106:109], v[208:211], v[156:159], v[106:109]
	v_mfma_f32_16x16x32_bf16 v[110:113], v[212:215], v[156:159], v[110:113]
	v_mfma_f32_16x16x32_bf16 v[114:117], v[188:191], v[160:163], v[114:117]
	v_mfma_f32_16x16x32_bf16 v[118:121], v[192:195], v[160:163], v[118:121]
	v_mfma_f32_16x16x32_bf16 v[122:125], v[208:211], v[160:163], v[122:125]
	v_mfma_f32_16x16x32_bf16 v[126:129], v[212:215], v[160:163], v[126:129]
	s_setprio 0
	s_waitcnt vmcnt(0)
	s_barrier
	ds_read_b128 v[148:151], v140 offset:16384
	ds_read_b128 v[152:155], v140 offset:18432
	ds_read_b128 v[156:159], v140 offset:20480
	ds_read_b128 v[160:163], v140 offset:22528
	ds_read_b128 v[164:167], v142 offset:32768
	ds_read_b128 v[168:171], v142 offset:34816
	ds_read_b128 v[174:177], v142 offset:36864
	ds_read_b128 v[182:185], v142 offset:38912
	ds_read_b128 v[188:191], v142 offset:49152
	ds_read_b128 v[192:195], v142 offset:51200
	ds_read_b128 v[208:211], v142 offset:53248
	ds_read_b128 v[212:215], v142 offset:55296
	s_waitcnt lgkmcnt(0)
	s_setprio 1
	v_mfma_f32_16x16x32_bf16 v[62:65], v[164:167], v[148:151], v[62:65]
	v_mfma_f32_16x16x32_bf16 v[58:61], v[168:171], v[148:151], v[58:61]
	v_mfma_f32_16x16x32_bf16 v[54:57], v[174:177], v[148:151], v[54:57]
	v_mfma_f32_16x16x32_bf16 v[50:53], v[182:185], v[148:151], v[50:53]
	v_mfma_f32_16x16x32_bf16 v[46:49], v[164:167], v[152:155], v[46:49]
	v_mfma_f32_16x16x32_bf16 v[42:45], v[168:171], v[152:155], v[42:45]
	v_mfma_f32_16x16x32_bf16 v[38:41], v[174:177], v[152:155], v[38:41]
	v_mfma_f32_16x16x32_bf16 v[34:37], v[182:185], v[152:155], v[34:37]
	v_mfma_f32_16x16x32_bf16 v[30:33], v[164:167], v[156:159], v[30:33]
	v_mfma_f32_16x16x32_bf16 v[26:29], v[168:171], v[156:159], v[26:29]
	v_mfma_f32_16x16x32_bf16 v[22:25], v[174:177], v[156:159], v[22:25]
	v_mfma_f32_16x16x32_bf16 v[18:21], v[182:185], v[156:159], v[18:21]
	v_mfma_f32_16x16x32_bf16 v[14:17], v[164:167], v[160:163], v[14:17]
	v_mfma_f32_16x16x32_bf16 v[10:13], v[168:171], v[160:163], v[10:13]
	v_mfma_f32_16x16x32_bf16 v[6:9], v[174:177], v[160:163], v[6:9]
	v_mfma_f32_16x16x32_bf16 v[2:5], v[182:185], v[160:163], v[2:5]
	v_mfma_f32_16x16x32_bf16 v[66:69], v[188:191], v[148:151], v[66:69]
	v_mfma_f32_16x16x32_bf16 v[70:73], v[192:195], v[148:151], v[70:73]
	v_mfma_f32_16x16x32_bf16 v[74:77], v[208:211], v[148:151], v[74:77]
	v_mfma_f32_16x16x32_bf16 v[78:81], v[212:215], v[148:151], v[78:81]
	v_mfma_f32_16x16x32_bf16 v[82:85], v[188:191], v[152:155], v[82:85]
	v_mfma_f32_16x16x32_bf16 v[86:89], v[192:195], v[152:155], v[86:89]
	v_mfma_f32_16x16x32_bf16 v[90:93], v[208:211], v[152:155], v[90:93]
	v_mfma_f32_16x16x32_bf16 v[94:97], v[212:215], v[152:155], v[94:97]
	v_mfma_f32_16x16x32_bf16 v[98:101], v[188:191], v[156:159], v[98:101]
	v_mfma_f32_16x16x32_bf16 v[102:105], v[192:195], v[156:159], v[102:105]
	v_mfma_f32_16x16x32_bf16 v[106:109], v[208:211], v[156:159], v[106:109]
	v_mfma_f32_16x16x32_bf16 v[110:113], v[212:215], v[156:159], v[110:113]
	v_mfma_f32_16x16x32_bf16 v[114:117], v[188:191], v[160:163], v[114:117]
	v_mfma_f32_16x16x32_bf16 v[118:121], v[192:195], v[160:163], v[118:121]
	v_mfma_f32_16x16x32_bf16 v[122:125], v[208:211], v[160:163], v[122:125]
	v_mfma_f32_16x16x32_bf16 v[126:129], v[212:215], v[160:163], v[126:129]
	s_setprio 0
	ds_read_b128 v[148:151], v141 offset:16384
	ds_read_b128 v[152:155], v141 offset:18432
	ds_read_b128 v[156:159], v141 offset:20480
	ds_read_b128 v[160:163], v141 offset:22528
	ds_read_b128 v[164:167], v143 offset:32768
	ds_read_b128 v[168:171], v143 offset:34816
	ds_read_b128 v[174:177], v143 offset:36864
	ds_read_b128 v[182:185], v143 offset:38912
	ds_read_b128 v[188:191], v143 offset:49152
	ds_read_b128 v[192:195], v143 offset:51200
	ds_read_b128 v[208:211], v143 offset:53248
	ds_read_b128 v[212:215], v143 offset:55296
	s_waitcnt lgkmcnt(0)
	s_setprio 1
	v_mfma_f32_16x16x32_bf16 v[62:65], v[164:167], v[148:151], v[62:65]
	v_mfma_f32_16x16x32_bf16 v[58:61], v[168:171], v[148:151], v[58:61]
	v_mfma_f32_16x16x32_bf16 v[54:57], v[174:177], v[148:151], v[54:57]
	v_mfma_f32_16x16x32_bf16 v[50:53], v[182:185], v[148:151], v[50:53]
	v_mfma_f32_16x16x32_bf16 v[46:49], v[164:167], v[152:155], v[46:49]
	v_mfma_f32_16x16x32_bf16 v[42:45], v[168:171], v[152:155], v[42:45]
	v_mfma_f32_16x16x32_bf16 v[38:41], v[174:177], v[152:155], v[38:41]
	v_mfma_f32_16x16x32_bf16 v[34:37], v[182:185], v[152:155], v[34:37]
	v_mfma_f32_16x16x32_bf16 v[30:33], v[164:167], v[156:159], v[30:33]
	v_mfma_f32_16x16x32_bf16 v[26:29], v[168:171], v[156:159], v[26:29]
	v_mfma_f32_16x16x32_bf16 v[22:25], v[174:177], v[156:159], v[22:25]
	v_mfma_f32_16x16x32_bf16 v[18:21], v[182:185], v[156:159], v[18:21]
	v_mfma_f32_16x16x32_bf16 v[14:17], v[164:167], v[160:163], v[14:17]
	v_mfma_f32_16x16x32_bf16 v[10:13], v[168:171], v[160:163], v[10:13]
	v_mfma_f32_16x16x32_bf16 v[6:9], v[174:177], v[160:163], v[6:9]
	v_mfma_f32_16x16x32_bf16 v[2:5], v[182:185], v[160:163], v[2:5]
	v_mfma_f32_16x16x32_bf16 v[66:69], v[188:191], v[148:151], v[66:69]
	v_mfma_f32_16x16x32_bf16 v[70:73], v[192:195], v[148:151], v[70:73]
	v_mfma_f32_16x16x32_bf16 v[74:77], v[208:211], v[148:151], v[74:77]
	v_mfma_f32_16x16x32_bf16 v[78:81], v[212:215], v[148:151], v[78:81]
	v_mfma_f32_16x16x32_bf16 v[82:85], v[188:191], v[152:155], v[82:85]
	v_mfma_f32_16x16x32_bf16 v[86:89], v[192:195], v[152:155], v[86:89]
	v_mfma_f32_16x16x32_bf16 v[90:93], v[208:211], v[152:155], v[90:93]
	v_mfma_f32_16x16x32_bf16 v[94:97], v[212:215], v[152:155], v[94:97]
	v_mfma_f32_16x16x32_bf16 v[98:101], v[188:191], v[156:159], v[98:101]
	v_mfma_f32_16x16x32_bf16 v[102:105], v[192:195], v[156:159], v[102:105]
	v_mfma_f32_16x16x32_bf16 v[106:109], v[208:211], v[156:159], v[106:109]
	v_mfma_f32_16x16x32_bf16 v[110:113], v[212:215], v[156:159], v[110:113]
	v_mfma_f32_16x16x32_bf16 v[114:117], v[188:191], v[160:163], v[114:117]
	v_mfma_f32_16x16x32_bf16 v[118:121], v[192:195], v[160:163], v[118:121]
	v_mfma_f32_16x16x32_bf16 v[122:125], v[208:211], v[160:163], v[122:125]
	v_mfma_f32_16x16x32_bf16 v[126:129], v[212:215], v[160:163], v[126:129]
	s_setprio 0
	v_lshrrev_b32_e32 v144, 7, v196
	v_and_b32_e32 v145, 15, v196
	v_lshl_or_b32 v144, v144, 6, v145
	v_lshlrev_b32_e32 v144, 12, v144
	v_bfe_u32 v145, v196, 6, 1
	v_bfe_u32 v146, v196, 4, 2
	v_lshlrev_b32_e32 v145, 8, v145
	v_lshl_or_b32 v145, v146, 4, v145
	v_add_u32_e32 v136, v144, v145
	v_add_u32_e32 v137, 0x10000, v136
	v_add_u32_e32 v138, 0x20000, v136
	v_add_u32_e32 v139, 0x30000, v136
	s_nop 7
	s_nop 7
	s_nop 7
	global_load_dwordx4 v[148:151], v136, s[40:41] offset:0
	global_load_dwordx4 v[152:155], v136, s[40:41] offset:64
	global_load_dwordx4 v[156:159], v136, s[40:41] offset:128
	global_load_dwordx4 v[160:163], v136, s[40:41] offset:192
	global_load_dwordx4 v[164:167], v137, s[40:41] offset:0
	global_load_dwordx4 v[168:171], v137, s[40:41] offset:64
	global_load_dwordx4 v[174:177], v137, s[40:41] offset:128
	global_load_dwordx4 v[182:185], v137, s[40:41] offset:192
	global_load_dwordx4 v[188:191], v138, s[40:41] offset:0
	global_load_dwordx4 v[192:195], v138, s[40:41] offset:64
	global_load_dwordx4 v[208:211], v138, s[40:41] offset:128
	global_load_dwordx4 v[212:215], v138, s[40:41] offset:192
	global_load_dwordx4 v[216:219], v139, s[40:41] offset:0
	global_load_dwordx4 v[220:223], v139, s[40:41] offset:64
	global_load_dwordx4 v[242:245], v139, s[40:41] offset:128
	global_load_dwordx4 v[144:147], v139, s[40:41] offset:192
	s_waitcnt vmcnt(0)
	v_pk_add_f32 v[62:63], v[62:63], v[148:149]
	v_pk_add_f32 v[64:65], v[64:65], v[150:151]
	v_pk_add_f32 v[58:59], v[58:59], v[152:153]
	v_pk_add_f32 v[60:61], v[60:61], v[154:155]
	v_pk_add_f32 v[54:55], v[54:55], v[156:157]
	v_pk_add_f32 v[56:57], v[56:57], v[158:159]
	v_pk_add_f32 v[50:51], v[50:51], v[160:161]
	v_pk_add_f32 v[52:53], v[52:53], v[162:163]
	v_pk_add_f32 v[46:47], v[46:47], v[164:165]
	v_pk_add_f32 v[48:49], v[48:49], v[166:167]
	v_pk_add_f32 v[42:43], v[42:43], v[168:169]
	v_pk_add_f32 v[44:45], v[44:45], v[170:171]
	v_pk_add_f32 v[38:39], v[38:39], v[174:175]
	v_pk_add_f32 v[40:41], v[40:41], v[176:177]
	v_pk_add_f32 v[34:35], v[34:35], v[182:183]
	v_pk_add_f32 v[36:37], v[36:37], v[184:185]
	v_pk_add_f32 v[30:31], v[30:31], v[188:189]
	v_pk_add_f32 v[32:33], v[32:33], v[190:191]
	v_pk_add_f32 v[26:27], v[26:27], v[192:193]
	v_pk_add_f32 v[28:29], v[28:29], v[194:195]
	v_pk_add_f32 v[22:23], v[22:23], v[208:209]
	v_pk_add_f32 v[24:25], v[24:25], v[210:211]
	v_pk_add_f32 v[18:19], v[18:19], v[212:213]
	v_pk_add_f32 v[20:21], v[20:21], v[214:215]
	v_pk_add_f32 v[14:15], v[14:15], v[216:217]
	v_pk_add_f32 v[16:17], v[16:17], v[218:219]
	v_pk_add_f32 v[10:11], v[10:11], v[220:221]
	v_pk_add_f32 v[12:13], v[12:13], v[222:223]
	v_pk_add_f32 v[6:7], v[6:7], v[242:243]
	v_pk_add_f32 v[8:9], v[8:9], v[244:245]
	v_pk_add_f32 v[2:3], v[2:3], v[144:145]
	v_pk_add_f32 v[4:5], v[4:5], v[146:147]
	global_load_dwordx4 v[148:151], v136, s[42:43] offset:0
	global_load_dwordx4 v[152:155], v136, s[42:43] offset:64
	global_load_dwordx4 v[156:159], v136, s[42:43] offset:128
	global_load_dwordx4 v[160:163], v136, s[42:43] offset:192
	global_load_dwordx4 v[164:167], v137, s[42:43] offset:0
	global_load_dwordx4 v[168:171], v137, s[42:43] offset:64
	global_load_dwordx4 v[174:177], v137, s[42:43] offset:128
	global_load_dwordx4 v[182:185], v137, s[42:43] offset:192
	global_load_dwordx4 v[188:191], v138, s[42:43] offset:0
	global_load_dwordx4 v[192:195], v138, s[42:43] offset:64
	global_load_dwordx4 v[208:211], v138, s[42:43] offset:128
	global_load_dwordx4 v[212:215], v138, s[42:43] offset:192
	global_load_dwordx4 v[216:219], v139, s[42:43] offset:0
	global_load_dwordx4 v[220:223], v139, s[42:43] offset:64
	global_load_dwordx4 v[242:245], v139, s[42:43] offset:128
	global_load_dwordx4 v[144:147], v139, s[42:43] offset:192
	global_store_dwordx4 v136, v[62:65], s[40:41] offset:0
	global_store_dwordx4 v136, v[58:61], s[40:41] offset:64
	global_store_dwordx4 v136, v[54:57], s[40:41] offset:128
	global_store_dwordx4 v136, v[50:53], s[40:41] offset:192
	global_store_dwordx4 v137, v[46:49], s[40:41] offset:0
	global_store_dwordx4 v137, v[42:45], s[40:41] offset:64
	global_store_dwordx4 v137, v[38:41], s[40:41] offset:128
	global_store_dwordx4 v137, v[34:37], s[40:41] offset:192
	global_store_dwordx4 v138, v[30:33], s[40:41] offset:0
	global_store_dwordx4 v138, v[26:29], s[40:41] offset:64
	global_store_dwordx4 v138, v[22:25], s[40:41] offset:128
	global_store_dwordx4 v138, v[18:21], s[40:41] offset:192
	global_store_dwordx4 v139, v[14:17], s[40:41] offset:0
	global_store_dwordx4 v139, v[10:13], s[40:41] offset:64
	global_store_dwordx4 v139, v[6:9], s[40:41] offset:128
	global_store_dwordx4 v139, v[2:5], s[40:41] offset:192
	s_waitcnt vmcnt(0)
	v_pk_add_f32 v[66:67], v[66:67], v[148:149]
	v_pk_add_f32 v[68:69], v[68:69], v[150:151]
	v_pk_add_f32 v[70:71], v[70:71], v[152:153]
	v_pk_add_f32 v[72:73], v[72:73], v[154:155]
	v_pk_add_f32 v[74:75], v[74:75], v[156:157]
	v_pk_add_f32 v[76:77], v[76:77], v[158:159]
	v_pk_add_f32 v[78:79], v[78:79], v[160:161]
	v_pk_add_f32 v[80:81], v[80:81], v[162:163]
	v_pk_add_f32 v[82:83], v[82:83], v[164:165]
	v_pk_add_f32 v[84:85], v[84:85], v[166:167]
	v_pk_add_f32 v[86:87], v[86:87], v[168:169]
	v_pk_add_f32 v[88:89], v[88:89], v[170:171]
	v_pk_add_f32 v[90:91], v[90:91], v[174:175]
	v_pk_add_f32 v[92:93], v[92:93], v[176:177]
	v_pk_add_f32 v[94:95], v[94:95], v[182:183]
	v_pk_add_f32 v[96:97], v[96:97], v[184:185]
	v_pk_add_f32 v[98:99], v[98:99], v[188:189]
	v_pk_add_f32 v[100:101], v[100:101], v[190:191]
	v_pk_add_f32 v[102:103], v[102:103], v[192:193]
	v_pk_add_f32 v[104:105], v[104:105], v[194:195]
	v_pk_add_f32 v[106:107], v[106:107], v[208:209]
	v_pk_add_f32 v[108:109], v[108:109], v[210:211]
	v_pk_add_f32 v[110:111], v[110:111], v[212:213]
	v_pk_add_f32 v[112:113], v[112:113], v[214:215]
	v_pk_add_f32 v[114:115], v[114:115], v[216:217]
	v_pk_add_f32 v[116:117], v[116:117], v[218:219]
	v_pk_add_f32 v[118:119], v[118:119], v[220:221]
	v_pk_add_f32 v[120:121], v[120:121], v[222:223]
	v_pk_add_f32 v[122:123], v[122:123], v[242:243]
	v_pk_add_f32 v[124:125], v[124:125], v[244:245]
	v_pk_add_f32 v[126:127], v[126:127], v[144:145]
	v_pk_add_f32 v[128:129], v[128:129], v[146:147]
	global_store_dwordx4 v136, v[66:69], s[42:43] offset:0
	global_store_dwordx4 v136, v[70:73], s[42:43] offset:64
	global_store_dwordx4 v136, v[74:77], s[42:43] offset:128
	global_store_dwordx4 v136, v[78:81], s[42:43] offset:192
	global_store_dwordx4 v137, v[82:85], s[42:43] offset:0
	global_store_dwordx4 v137, v[86:89], s[42:43] offset:64
	global_store_dwordx4 v137, v[90:93], s[42:43] offset:128
	global_store_dwordx4 v137, v[94:97], s[42:43] offset:192
	global_store_dwordx4 v138, v[98:101], s[42:43] offset:0
	global_store_dwordx4 v138, v[102:105], s[42:43] offset:64
	global_store_dwordx4 v138, v[106:109], s[42:43] offset:128
	global_store_dwordx4 v138, v[110:113], s[42:43] offset:192
	global_store_dwordx4 v139, v[114:117], s[42:43] offset:0
	global_store_dwordx4 v139, v[118:121], s[42:43] offset:64
	global_store_dwordx4 v139, v[122:125], s[42:43] offset:128
	global_store_dwordx4 v139, v[126:129], s[42:43] offset:192
	s_branch .LBB0_2421
